# pe-bias partial-sum loop in weight prep: 16 products per trip with batched loads
# baseline (speedup 1.0000x reference)
; __device__ __forceinline__ void prep_weights(lptr L, const Params& P, int l) {
;     ...
;     if (blockIdx.x < 32) {
;         const int src = blockIdx.x >> 4, part = (blockIdx.x & 15) * 2 + (tid >> 8), n = tid & 255;
;         const float* pe = (src ? P.in[8] : P.in[7]) + (size_t)l * 2048; const float* w1 = (src ? P.in[11] : P.in[9]) + (size_t)l * 2048 * 256;
;         float s = 0.f;
;         for (int k = 64 * part; k < 64 * part + 64; ++k) s += pe[k] * w1[(size_t)k * 256 + n];
;         ((float*)(ws + W_PEB))[(src * 32 + part) * 256 + n] = s;
;     }
.LBB0_939:
	s_mov_b64 s[2:3], 0x1000
	s_mov_b32 s26, 4
.Lpeb_loop:
	global_load_dword v20, v[2:3], off
	global_load_dword v21, v[2:3], off offset:4
	global_load_dword v22, v[2:3], off offset:8
	global_load_dword v23, v[2:3], off offset:12
	global_load_dword v24, v[2:3], off offset:16
	global_load_dword v25, v[2:3], off offset:20
	global_load_dword v26, v[2:3], off offset:24
	global_load_dword v27, v[2:3], off offset:28
	global_load_dword v28, v[2:3], off offset:32
	global_load_dword v29, v[2:3], off offset:36
	global_load_dword v30, v[2:3], off offset:40
	global_load_dword v31, v[2:3], off offset:44
	global_load_dword v32, v[2:3], off offset:48
	global_load_dword v33, v[2:3], off offset:52
	global_load_dword v34, v[2:3], off offset:56
	global_load_dword v35, v[2:3], off offset:60
	global_load_dword v36, v[4:5], off
	global_load_dword v37, v[4:5], off offset:1024
	global_load_dword v38, v[4:5], off offset:2048
	global_load_dword v39, v[4:5], off offset:3072
	v_lshl_add_u64 v[4:5], v[4:5], 0, s[2:3]
	global_load_dword v40, v[4:5], off
	global_load_dword v41, v[4:5], off offset:1024
	global_load_dword v42, v[4:5], off offset:2048
	global_load_dword v43, v[4:5], off offset:3072
	v_lshl_add_u64 v[4:5], v[4:5], 0, s[2:3]
	global_load_dword v44, v[4:5], off
	global_load_dword v45, v[4:5], off offset:1024
	global_load_dword v46, v[4:5], off offset:2048
	global_load_dword v47, v[4:5], off offset:3072
	v_lshl_add_u64 v[4:5], v[4:5], 0, s[2:3]
	global_load_dword v48, v[4:5], off
	global_load_dword v49, v[4:5], off offset:1024
	global_load_dword v50, v[4:5], off offset:2048
	global_load_dword v51, v[4:5], off offset:3072
	v_lshl_add_u64 v[4:5], v[4:5], 0, s[2:3]
	v_lshl_add_u64 v[2:3], v[2:3], 0, 64
	s_waitcnt vmcnt(0)
	v_fmac_f32_e32 v9, v20, v36
	v_fmac_f32_e32 v9, v21, v37
	v_fmac_f32_e32 v9, v22, v38
	v_fmac_f32_e32 v9, v23, v39
	v_fmac_f32_e32 v9, v24, v40
	v_fmac_f32_e32 v9, v25, v41
	v_fmac_f32_e32 v9, v26, v42
	v_fmac_f32_e32 v9, v27, v43
	v_fmac_f32_e32 v9, v28, v44
	v_fmac_f32_e32 v9, v29, v45
	v_fmac_f32_e32 v9, v30, v46
	v_fmac_f32_e32 v9, v31, v47
	v_fmac_f32_e32 v9, v32, v48
	v_fmac_f32_e32 v9, v33, v49
	v_fmac_f32_e32 v9, v34, v50
	v_fmac_f32_e32 v9, v35, v51
	s_sub_i32 s26, s26, 1
	s_cmp_lg_u32 s26, 0
	s_cbranch_scc1 .Lpeb_loop
	s_or_b64 exec, exec, s[0:1]
	v_readlane_b32 s0, v253, 28
	s_nop 1
	v_add_u32_e32 v0, s0, v0
	v_lshl_or_b32 v2, v0, 8, v6
	v_readlane_b32 s0, v253, 26
	v_ashrrev_i32_e32 v3, 31, v2
	v_readlane_b32 s1, v253, 27
	s_nop 1
	v_lshl_add_u64 v[2:3], v[2:3], 2, s[0:1]
	global_store_dword v[2:3], v9, off
